# attention: K/V global->LDS staging through free AGPRs, 4th score tile in VGPRs (all accvgpr reads gone from the tile loop)
# speedup vs baseline: 1.0714x; 1.0073x over previous
; template <bool SAMPLE>
; DEV void attn_unit(CParams& p, int layer, int unit, float lam, float lam_init, char* lds, const int swave) {
;     ...
;   for (int t = 0; t < ntiles; ++t) {
;     const int tn = SAMPLE ? t + 1 : (t + 1 < ntiles ? t + 1 : t);
;     if (!SAMPLE || t + 1 < ntiles) gloadK(tn);
;     if (t < my_tiles) {
;       const char* Ks = lds + (t & 1) * A_BUF; const char* Vs = Ks + A_KT;
;       bf16x8 pf[2][4];
;       f32x16 S0, S1;
;       auto qk = [&](int br) {
;         const f32x16 zc = {0.f, 0.f, 0.f, 0.f, 0.f, 0.f, 0.f, 0.f, 0.f, 0.f, 0.f, 0.f, 0.f, 0.f, 0.f, 0.f};
; #pragma unroll
;         for (int ks = 0; ks < 4; ++ks) {
;           const bf16x8 k0 = lds_read8(Ks + lr * AK_B + (br * 64 + ks * 16 + hh * 8) * 2);
;           const bf16x8 k1 = lds_read8(Ks + (32 + lr) * AK_B + (br * 64 + ks * 16 + hh * 8) * 2);
;           S0 = mfma32(k0, qf[br][ks], ks == 0 ? zc : S0); S1 = mfma32(k1, qf[br][ks], ks == 0 ? zc : S1);
;         }
;         if (sample && t == 32) {
; #pragma unroll
;           for (int r = 0; r < 16; ++r) { if (r >= 8) S0[r] = -1e30f; S1[r] = -1e30f; }
;         }
;       };
;       auto sm8 = [&](const f32x16& Sx, int r0, float nm, float& lsum) -> bf16x8 {
;         f32x2 c2; c2[0] = cexp; c2[1] = cexp;
;         f32x2 nm2; nm2[0] = nm; nm2[1] = nm;
;         union { u32x4 u; bf16x8 b; } x;
;         f32x2 sum2; sum2[0] = 0.f; sum2[1] = 0.f;
; #pragma unroll
;         for (int r = 0; r < 8; r += 2) {
;           f32x2 v; v[0] = Sx[r0 + r]; v[1] = Sx[r0 + r + 1];
;           v = v * c2 + nm2;
;           f32x2 ex; ex[0] = __builtin_amdgcn_exp2f(v[0]); ex[1] = __builtin_amdgcn_exp2f(v[1]);
;           sum2 += ex;
;           x.u[r >> 1] = pk2(ex[0], ex[1]);
;         }
;         lsum += sum2[0] + sum2[1];
;         return x.b;
;       };
;       qk(0);
;       pf[0][0] = sm8(S0, 0, nmc[0], ls[0]); pf[0][1] = sm8(S0, 8, nmc[0], ls[0]);
;       pf[0][2] = sm8(S1, 0, nmc[0], ls[0]); pf[0][3] = sm8(S1, 8, nmc[0], ls[0]);
;       qk(1);
;       if (!SAMPLE || t + 1 < ntiles) gloadV(tn);
; #pragma unroll
;       for (int sl = 0; sl < 4; ++sl) {
; #pragma unroll
;         for (int e = 0; e < 4; ++e) {
;           const bf16x8 vf = tr8(Vs, AV_B, sl * 16, e * 32, lane);
;           O1[e] = mfma32(vf, pf[0][sl], O1[e]);
;         }
;         pf[1][sl] = sm8(sl < 2 ? S0 : S1, (sl & 1) * 8, nmc[1], ls[1]);
.LBB0_243:
	s_add_i32 s36, s37, 1
	s_cmp_ge_u32 s36, s23
	s_cselect_b64 s[6:7], -1, 0
	s_cmp_lt_u32 s36, s23
	s_cselect_b32 s100, s36, s37
	s_lshl_b32 s101, s100, 6
	s_cmp_ge_u32 s37, s29
	s_cbranch_scc1 .LBB0_245
	s_bitcmp1_b32 s37, 0
	s_cselect_b32 s38, 0x9400, 0
	s_add_i32 s38, s38, 16
	v_add_u32_e32 v118, s38, v243
	ds_read_b128 v[62:65], v118
	ds_read_b128 v[66:69], v118 offset:32
	s_waitcnt lgkmcnt(1)
	v_mfma_f32_32x32x16_bf16 v[178:193], v[62:65], v[16:19], 0
	s_add_i32 s8, s101, s28
	s_mul_hi_i32 s9, s8, 0xc00
	s_mulk_i32 s8, 0xc00
	s_or_b64 s[8:9], s[8:9], s[2:3]
	v_lshl_add_u64 v[54:55], s[8:9], 1, v[50:51]
	global_load_dwordx4 a[160:163], v[54:55], off
	global_load_dwordx4 a[144:147], v[54:55], off offset:1024
	ds_read_b128 v[62:65], v118 offset:8704
	ds_read_b128 v[70:73], v118 offset:8736
	s_waitcnt lgkmcnt(1)
	v_mfma_f32_32x32x16_bf16 v[210:225], v[62:65], v[16:19], 0
	s_add_i32 s8, s30, s101
	s_mul_hi_i32 s9, s8, 0xc00
	s_mulk_i32 s8, 0xc00
	s_or_b64 s[8:9], s[8:9], s[2:3]
	v_lshl_add_u64 v[56:57], s[8:9], 1, v[50:51]
	global_load_dwordx4 a[164:167], v[56:57], off
	global_load_dwordx4 a[148:151], v[56:57], off offset:1024
	v_mfma_f32_32x32x16_bf16 v[178:193], v[66:69], v[20:23], v[178:193]
	s_add_i32 s8, s31, s101
	s_mul_hi_i32 s9, s8, 0xc00
	s_mulk_i32 s8, 0xc00
	s_or_b64 s[8:9], s[8:9], s[2:3]
	v_lshl_add_u64 v[58:59], s[8:9], 1, v[50:51]
	global_load_dwordx4 a[168:171], v[58:59], off
	global_load_dwordx4 a[152:155], v[58:59], off offset:1024
	ds_read_b128 v[62:65], v118 offset:64
	ds_read_b128 v[66:69], v118 offset:96
	s_waitcnt lgkmcnt(2)
	v_mfma_f32_32x32x16_bf16 v[210:225], v[70:73], v[20:23], v[210:225]
	s_add_i32 s8, s34, s101
	s_mul_hi_i32 s9, s8, 0xc00
	s_mulk_i32 s8, 0xc00
	s_or_b64 s[8:9], s[8:9], s[2:3]
	v_lshl_add_u64 v[60:61], s[8:9], 1, v[50:51]
	global_load_dwordx4 a[172:175], v[60:61], off
	global_load_dwordx4 a[156:159], v[60:61], off offset:1024
	s_waitcnt lgkmcnt(1)
	v_mfma_f32_32x32x16_bf16 v[178:193], v[62:65], v[24:27], v[178:193]
	ds_read_b128 v[62:65], v118 offset:8768
	ds_read_b128 v[70:73], v118 offset:8800
	ds_read_b128 v[88:91], v118 offset:128
	s_waitcnt lgkmcnt(2)
	v_mfma_f32_32x32x16_bf16 v[210:225], v[62:65], v[24:27], v[210:225]
	s_waitcnt lgkmcnt(0)
	v_mfma_f32_32x32x16_bf16 v[226:241], v[88:91], v[32:35], 0
	v_mfma_f32_32x32x16_bf16 v[178:193], v[66:69], v[28:31], v[178:193]
	s_nop 11
	v_fma_f32 v102, v180, s52, v48
	v_fma_f32 v103, v181, s52, v49
	v_fma_f32 v62, v184, s52, v48
	v_fma_f32 v63, v185, s52, v49
	v_fma_f32 v66, v190, s52, v48
	v_fma_f32 v67, v191, s52, v49
	v_mfma_f32_32x32x16_bf16 v[210:225], v[70:73], v[28:31], v[210:225]
	ds_read_b128 v[68:71], v118 offset:8832
	ds_read_b128 v[92:95], v118 offset:160
	ds_read_b128 v[88:91], v118 offset:8864
	s_waitcnt lgkmcnt(2)
	v_exp_f32_e32 v66, v66
	v_mfma_f32_32x32x16_bf16 v[194:209], v[68:71], v[32:35], 0
	s_waitcnt lgkmcnt(1)
	v_exp_f32_e32 v67, v67
	v_fma_f32 v64, v192, s52, v48
	v_fma_f32 v65, v193, s52, v49
	s_nop 1
	v_fma_f32 v74, v218, s52, v48
	v_mfma_f32_32x32x16_bf16 v[226:241], v[92:95], v[36:39], v[226:241]
	ds_read_b128 v[92:95], v118 offset:192
	s_waitcnt lgkmcnt(1)
	v_fma_f32 v75, v219, s52, v49
	v_fma_f32 v72, v220, s52, v48
	v_fma_f32 v73, v221, s52, v49
	v_exp_f32_e32 v74, v74
	v_mfma_f32_32x32x16_bf16 v[194:209], v[88:91], v[36:39], v[194:209]
	v_fma_f32 v88, v178, s52, v48
	v_fma_f32 v89, v179, s52, v49
	v_exp_f32_e32 v100, v88
	v_exp_f32_e32 v101, v89
	ds_read_b128 v[88:91], v118 offset:8896
	ds_read_b128 v[96:99], v118 offset:224
	s_waitcnt lgkmcnt(2)
	v_mfma_f32_32x32x16_bf16 v[226:241], v[92:95], v[40:43], v[226:241]
	v_exp_f32_e32 v94, v102
	v_exp_f32_e32 v95, v103
	v_cvt_pk_bf16_f32 v92, v100, v101
	v_add_f32_e32 v116, v94, v100
	v_add_f32_e32 v117, v95, v101
	ds_read_b128 v[100:103], v118 offset:8928
	s_waitcnt lgkmcnt(2)
	v_mfma_f32_32x32x16_bf16 v[194:209], v[88:91], v[40:43], v[194:209]
	v_add3_u32 v108, s38, v87, v86
	v_fma_f32 v88, v182, s52, v48
	v_fma_f32 v89, v183, s52, v49
	v_exp_f32_e32 v90, v62
	v_exp_f32_e32 v88, v88
	v_exp_f32_e32 v89, v89
	v_exp_f32_e32 v91, v63
	v_add_f32_e32 v62, v88, v116
	v_add_f32_e32 v63, v89, v117
	ds_read_b64_tr_b16 v[116:117], v108 offset:17408
	ds_read_b64_tr_b16 v[118:119], v108 offset:19968
	s_waitcnt lgkmcnt(2)
	v_mfma_f32_32x32x16_bf16 v[194:209], v[100:103], v[44:47], v[194:209]
	ds_read_b64_tr_b16 v[100:101], v108 offset:17472
	ds_read_b64_tr_b16 v[122:123], v108 offset:17536
	ds_read_b64_tr_b16 v[142:143], v108 offset:17600
	ds_read_b64_tr_b16 v[102:103], v108 offset:20032
	ds_read_b64_tr_b16 v[124:125], v108 offset:20096
	ds_read_b64_tr_b16 v[144:145], v108 offset:20160
	v_mfma_f32_32x32x16_bf16 v[226:241], v[96:99], v[44:47], v[226:241]
	s_waitcnt lgkmcnt(6)
	v_cvt_pk_bf16_f32 v93, v94, v95
	v_cvt_pk_bf16_f32 v94, v88, v89
	v_cvt_pk_bf16_f32 v95, v90, v91
	v_fma_f32 v88, v186, s52, v48
	v_fma_f32 v89, v187, s52, v49
	v_mfma_f32_32x32x16_bf16 a[0:15], v[116:119], v[92:95], a[0:15]
	ds_read_b64_tr_b16 v[146:147], v108 offset:22528
	ds_read_b64_tr_b16 v[148:149], v108 offset:25088
	s_waitcnt lgkmcnt(4)
	v_add_f32_e32 v62, v90, v62
	v_add_f32_e32 v63, v91, v63
	v_exp_f32_e32 v88, v88
	v_mfma_f32_32x32x16_bf16 a[32:47], v[100:103], v[92:95], a[32:47]
	ds_read_b64_tr_b16 v[150:151], v108 offset:22592
	ds_read_b64_tr_b16 v[154:155], v108 offset:22656
	ds_read_b64_tr_b16 v[158:159], v108 offset:22720
	ds_read_b64_tr_b16 v[152:153], v108 offset:25152
	ds_read_b64_tr_b16 v[156:157], v108 offset:25216
	ds_read_b64_tr_b16 v[160:161], v108 offset:25280
	s_waitcnt lgkmcnt(9)
	v_mfma_f32_32x32x16_bf16 a[64:79], v[122:125], v[92:95], a[64:79]
	s_waitcnt lgkmcnt(8)
; DEV uint32_t pk2(float lo, float hi) { f32x2 v; v[0] = lo; v[1] = hi; bf16v2 b = __builtin_convertvector(v, bf16v2); return __builtin_bit_cast(uint32_t, b); }
; DEV f32x16 mfma32(bf16x8 a, bf16x8 b, f32x16 c) { return __builtin_amdgcn_mfma_f32_32x32x16_bf16(a, b, c, 0, 0, 0); }
; template <bool SAMPLE>
; DEV void attn_unit(CParams& p, int layer, int unit, float lam, float lam_init, char* lds, const int swave) {
;     ...
;       auto sm8 = [&](const f32x16& Sx, int r0, float nm, float& lsum) -> bf16x8 {
;         f32x2 c2; c2[0] = cexp; c2[1] = cexp;
;         f32x2 nm2; nm2[0] = nm; nm2[1] = nm;
;         union { u32x4 u; bf16x8 b; } x;
;         f32x2 sum2; sum2[0] = 0.f; sum2[1] = 0.f;
; #pragma unroll
;         for (int r = 0; r < 8; r += 2) {
;           f32x2 v; v[0] = Sx[r0 + r]; v[1] = Sx[r0 + r + 1];
;           v = v * c2 + nm2;
;           f32x2 ex; ex[0] = __builtin_amdgcn_exp2f(v[0]); ex[1] = __builtin_amdgcn_exp2f(v[1]);
;           sum2 += ex;
;           x.u[r >> 1] = pk2(ex[0], ex[1]);
;         }
;         lsum += sum2[0] + sum2[1];
;         return x.b;
;       };
;       qk(0);
;       pf[0][0] = sm8(S0, 0, nmc[0], ls[0]); pf[0][1] = sm8(S0, 8, nmc[0], ls[0]);
;       pf[0][2] = sm8(S1, 0, nmc[0], ls[0]); pf[0][3] = sm8(S1, 8, nmc[0], ls[0]);
;       qk(1);
;       if (!SAMPLE || t + 1 < ntiles) gloadV(tn);
; #pragma unroll
;       for (int sl = 0; sl < 4; ++sl) {
; #pragma unroll
;         for (int e = 0; e < 4; ++e) {
;           const bf16x8 vf = tr8(Vs, AV_B, sl * 16, e * 32, lane);
;           O1[e] = mfma32(vf, pf[0][sl], O1[e]);
;         }
;         pf[1][sl] = sm8(sl < 2 ? S0 : S1, (sl & 1) * 8, nmc[1], ls[1]);
;       }
; #pragma unroll
;       for (int sl = 0; sl < 4; ++sl)
; #pragma unroll
;         for (int e = 0; e < 4; ++e) {
;           const bf16x8 vf = tr8(Vs, AV_B, sl * 16, e * 32, lane);
;           O2[e] = mfma32(vf, pf[1][sl], O2[e]);
;         }
	v_exp_f32_e32 v89, v89
	v_fma_f32 v90, v188, s52, v48
	v_fma_f32 v91, v189, s52, v49
	v_exp_f32_e32 v90, v90
	v_mfma_f32_32x32x16_bf16 a[96:111], v[142:145], v[92:95], a[96:111]
	ds_read_b64_tr_b16 v[162:163], v108 offset:27648
	ds_read_b64_tr_b16 v[164:165], v108 offset:30208
	s_waitcnt lgkmcnt(8)
	v_exp_f32_e32 v91, v91
	v_add_f32_e64 v96, v88, 0
	v_cvt_pk_bf16_f32 v88, v88, v89
	v_add_f32_e32 v96, v90, v96
	v_add_f32_e32 v97, v91, v89
	v_exp_f32_e32 v98, v64
	v_exp_f32_e32 v99, v65
	v_cvt_pk_bf16_f32 v89, v90, v91
	v_cvt_pk_bf16_f32 v90, v66, v67
	v_cvt_pk_bf16_f32 v91, v98, v99
	v_add_f32_e32 v64, v66, v96
	v_add_f32_e32 v65, v67, v97
	v_mfma_f32_32x32x16_bf16 a[0:15], v[146:149], v[88:91], a[0:15]
	ds_read_b64_tr_b16 v[166:167], v108 offset:27712
	ds_read_b64_tr_b16 v[170:171], v108 offset:27776
	ds_read_b64_tr_b16 v[174:175], v108 offset:27840
	ds_read_b64_tr_b16 v[168:169], v108 offset:30272
	ds_read_b64_tr_b16 v[172:173], v108 offset:30336
	ds_read_b64_tr_b16 v[176:177], v108 offset:30400
	s_waitcnt lgkmcnt(10)
	v_mfma_f32_32x32x16_bf16 a[32:47], v[150:153], v[88:91], a[32:47]
	s_waitcnt lgkmcnt(9)
	v_fma_f32 v66, v210, s52, v48
	v_fma_f32 v67, v211, s52, v49
	v_exp_f32_e32 v66, v66
	v_exp_f32_e32 v67, v67
	v_mfma_f32_32x32x16_bf16 a[64:79], v[154:157], v[88:91], a[64:79]
	s_waitcnt lgkmcnt(8)
	v_add_f32_e32 v64, v98, v64
	v_add_f32_e32 v65, v99, v65
	v_fma_f32 v98, v216, s52, v48
	v_fma_f32 v99, v217, s52, v49
	v_fma_f32 v92, v212, s52, v48
	v_mfma_f32_32x32x16_bf16 a[96:111], v[158:161], v[88:91], a[96:111]
	s_waitcnt lgkmcnt(6)
	v_fma_f32 v93, v213, s52, v49
	v_exp_f32_e32 v98, v98
	v_exp_f32_e32 v94, v92
	v_exp_f32_e32 v95, v93
	v_cvt_pk_bf16_f32 v92, v66, v67
	v_exp_f32_e32 v99, v99
	v_add_f32_e64 v66, v94, v66
	v_add_f32_e64 v67, v95, v67
	v_fma_f32 v96, v214, s52, v48
	v_fma_f32 v97, v215, s52, v49
	v_exp_f32_e32 v96, v96
	v_exp_f32_e32 v97, v97
	v_cvt_pk_bf16_f32 v93, v94, v95
	v_cvt_pk_bf16_f32 v94, v96, v97
	v_cvt_pk_bf16_f32 v95, v98, v99
	v_exp_f32_e32 v75, v75
	v_fma_f32 v70, v222, s52, v48
	v_mfma_f32_32x32x16_bf16 a[0:15], v[162:165], v[92:95], a[0:15]
	ds_read_b64_tr_b16 v[178:179], v108 offset:32768
	ds_read_b64_tr_b16 v[180:181], v108 offset:35328
	ds_read_b64_tr_b16 v[182:183], v108 offset:32832
	ds_read_b64_tr_b16 v[186:187], v108 offset:32896
	ds_read_b64_tr_b16 v[190:191], v108 offset:32960
	ds_read_b64_tr_b16 v[184:185], v108 offset:35392
	ds_read_b64_tr_b16 v[188:189], v108 offset:35456
	ds_read_b64_tr_b16 v[192:193], v108 offset:35520
	s_waitcnt lgkmcnt(10)
	v_mfma_f32_32x32x16_bf16 a[32:47], v[166:169], v[92:95], a[32:47]
	s_waitcnt lgkmcnt(9)
	v_fma_f32 v71, v223, s52, v49
	v_exp_f32_e32 v88, v72
	v_exp_f32_e32 v89, v73
	v_mfma_f32_32x32x16_bf16 a[64:79], v[170:173], v[92:95], a[64:79]
	s_waitcnt lgkmcnt(8)
	v_exp_f32_e32 v70, v70
	v_exp_f32_e32 v71, v71
	v_fma_f32 v68, v224, s52, v48
	v_mfma_f32_32x32x16_bf16 a[96:111], v[174:177], v[92:95], a[96:111]
	s_waitcnt lgkmcnt(6)
	v_fma_f32 v69, v225, s52, v49
	v_cvt_pk_bf16_f32 v72, v74, v75
	v_add_f32_e64 v74, v88, v74
	v_add_f32_e64 v75, v89, v75
	v_exp_f32_e32 v90, v68
	v_exp_f32_e32 v91, v69
	v_add_f32_e32 v68, v70, v74
	v_add_f32_e32 v69, v71, v75
	v_cvt_pk_bf16_f32 v74, v70, v71
	v_cvt_pk_bf16_f32 v73, v88, v89
	v_cvt_pk_bf16_f32 v75, v90, v91
	v_add_f32_e32 v66, v96, v66
	v_add_f32_e32 v67, v97, v67
	v_mfma_f32_32x32x16_bf16 a[0:15], v[178:181], v[72:75], a[0:15]
	s_waitcnt lgkmcnt(2)
	v_add_f32_e64 v66, v98, v66
	v_add_f32_e64 v67, v99, v67
	v_fma_f32 v98, v226, s52, v52
	v_fma_f32 v99, v227, s52, v53
	v_fma_f32 v96, v228, s52, v52
	v_mfma_f32_32x32x16_bf16 a[32:47], v[182:185], v[72:75], a[32:47]
	s_waitcnt lgkmcnt(1)
	v_fma_f32 v97, v229, s52, v53
	v_fma_f32 v70, v232, s52, v52
	v_fma_f32 v71, v233, s52, v53
	v_exp_f32_e32 v104, v98
	v_mfma_f32_32x32x16_bf16 a[64:79], v[186:189], v[72:75], a[64:79]
	s_waitcnt lgkmcnt(0)
	v_fma_f32 v94, v230, s52, v52
	v_fma_f32 v95, v231, s52, v53
	v_exp_f32_e32 v105, v99
	v_exp_f32_e32 v106, v96
	v_mfma_f32_32x32x16_bf16 a[96:111], v[190:193], v[72:75], a[96:111]
	v_exp_f32_e32 v107, v97
	v_exp_f32_e32 v108, v94
	v_exp_f32_e32 v109, v95
	v_exp_f32_e32 v74, v70
	v_exp_f32_e32 v75, v71
	v_cvt_pk_bf16_f32 v70, v104, v105
	v_cvt_pk_bf16_f32 v71, v106, v107
	v_cvt_pk_bf16_f32 v72, v108, v109
	v_cvt_pk_bf16_f32 v73, v74, v75
	v_add_f32_e32 v68, v90, v68
	v_add_f32_e32 v69, v91, v69
	v_mfma_f32_32x32x16_bf16 a[16:31], v[116:119], v[70:73], a[16:31]
	v_fma_f32 v94, v234, s52, v52
	v_fma_f32 v95, v235, s52, v53
	v_fma_f32 v92, v236, s52, v52
	v_fma_f32 v93, v237, s52, v53
	v_fma_f32 v90, v238, s52, v52
	v_fma_f32 v91, v239, s52, v53
	v_mfma_f32_32x32x16_bf16 a[48:63], v[100:103], v[70:73], a[48:63]
	v_exp_f32_e32 v120, v94
	v_exp_f32_e32 v121, v95
	v_mfma_f32_32x32x16_bf16 a[80:95], v[122:125], v[70:73], a[80:95]
	v_fma_f32 v132, v198, s52, v52
	v_fma_f32 v133, v199, s52, v53
	v_exp_f32_e32 v132, v132
	v_mfma_f32_32x32x16_bf16 a[112:127], v[142:145], v[70:73], a[112:127]
	v_cvt_pk_bf16_f32 v100, v120, v121
	v_exp_f32_e32 v122, v92
	v_exp_f32_e32 v123, v93
	v_exp_f32_e32 v124, v90
	v_exp_f32_e32 v125, v91
	v_cvt_pk_bf16_f32 v101, v122, v123
	v_fma_f32 v70, v240, s52, v52
	v_fma_f32 v71, v241, s52, v53
	v_cvt_pk_bf16_f32 v102, v124, v125
	v_exp_f32_e32 v126, v70
	v_exp_f32_e32 v127, v71
	s_nop 0
	v_cvt_pk_bf16_f32 v103, v126, v127
	v_add_f32_e64 v104, v106, v104
	v_add_f32_e64 v105, v107, v105
	v_mfma_f32_32x32x16_bf16 a[16:31], v[146:149], v[100:103], a[16:31]
	v_add_f32_e32 v104, v108, v104
	v_add_f32_e32 v105, v109, v105
	v_mfma_f32_32x32x16_bf16 a[48:63], v[150:153], v[100:103], a[48:63]
	v_fma_f32 v106, v194, s52, v52
	v_fma_f32 v107, v195, s52, v53
	v_fma_f32 v108, v196, s52, v52
	v_fma_f32 v109, v197, s52, v53
	v_exp_f32_e32 v106, v106
	v_mfma_f32_32x32x16_bf16 a[80:95], v[154:157], v[100:103], a[80:95]
	s_andn2_b32 s8, 1, s37
	s_mul_i32 s8, s8, 0x9400
	s_add_i32 s8, s8, 16
	s_waitcnt vmcnt(0)
; DEV f32x16 mfma32(bf16x8 a, bf16x8 b, f32x16 c) { return __builtin_amdgcn_mfma_f32_32x32x16_bf16(a, b, c, 0, 0, 0); }
; template <bool SAMPLE>
; DEV void attn_unit(CParams& p, int layer, int unit, float lam, float lam_init, char* lds, const int swave) {
;     ...
;       if (!SAMPLE || t + 1 < ntiles) gloadV(tn);
; #pragma unroll
;       for (int sl = 0; sl < 4; ++sl) {
; #pragma unroll
;         for (int e = 0; e < 4; ++e) {
;           const bf16x8 vf = tr8(Vs, AV_B, sl * 16, e * 32, lane);
;           O1[e] = mfma32(vf, pf[0][sl], O1[e]);
;         }
;         pf[1][sl] = sm8(sl < 2 ? S0 : S1, (sl & 1) * 8, nmc[1], ls[1]);
;       }
; #pragma unroll
;       for (int sl = 0; sl < 4; ++sl)
; #pragma unroll
;         for (int e = 0; e < 4; ++e) {
;           const bf16x8 vf = tr8(Vs, AV_B, sl * 16, e * 32, lane);
;           O2[e] = mfma32(vf, pf[1][sl], O2[e]);
;         }
;     }
;     if (t >= my_tiles && (!SAMPLE || t + 1 < ntiles)) gloadV(tn);
;     if (!SAMPLE || t + 1 < ntiles) lwrite((t + 1) & 1);
;     __syncthreads();
	v_add3_u32 v54, s8, v77, v76
	ds_write_b128 v54, a[160:163]
	v_add3_u32 v55, s8, v78, v76
	ds_write_b128 v55, a[144:147] offset:17408
	v_mfma_f32_32x32x16_bf16 a[112:127], v[158:161], v[100:103], a[112:127]
	v_add3_u32 v56, s8, v79, v76
	ds_write_b128 v56, a[164:167]
	v_add3_u32 v57, s8, v80, v76
	ds_write_b128 v57, a[148:151] offset:17408
	v_exp_f32_e32 v107, v107
	v_exp_f32_e32 v108, v108
	v_exp_f32_e32 v109, v109
	v_exp_f32_e32 v133, v133
	v_fma_f32 v100, v200, s52, v52
	v_fma_f32 v101, v201, s52, v53
	v_cvt_pk_bf16_f32 v102, v132, v133
	v_exp_f32_e32 v118, v100
	v_exp_f32_e32 v119, v101
	v_cvt_pk_bf16_f32 v100, v106, v107
	v_cvt_pk_bf16_f32 v101, v108, v109
	v_cvt_pk_bf16_f32 v103, v118, v119
	v_add_f32_e32 v74, v74, v104
	v_add_f32_e32 v75, v75, v105
	v_mfma_f32_32x32x16_bf16 a[16:31], v[162:165], v[100:103], a[16:31]
	v_add_f32_e32 v104, v122, v120
	v_add_f32_e32 v105, v123, v121
	v_add_f32_e64 v104, v124, v104
	v_add_f32_e64 v105, v125, v105
	v_mfma_f32_32x32x16_bf16 a[48:63], v[166:169], v[100:103], a[48:63]
	v_add_f32_e64 v120, v126, v104
	v_add_f32_e64 v121, v127, v105
	v_mfma_f32_32x32x16_bf16 a[80:95], v[170:173], v[100:103], a[80:95]
	v_add3_u32 v58, s8, v81, v76
	ds_write_b128 v58, a[168:171]
	v_add3_u32 v59, s8, v82, v76
	ds_write_b128 v59, a[152:155] offset:17408
	v_add_f32_e64 v104, v108, v106
	v_mfma_f32_32x32x16_bf16 a[112:127], v[174:177], v[100:103], a[112:127]
	v_add3_u32 v60, s8, v83, v76
	ds_write_b128 v60, a[172:175]
	v_add3_u32 v61, s8, v84, v76
	ds_write_b128 v61, a[156:159] offset:17408
	v_add_f32_e64 v105, v109, v107
	v_fma_f32 v112, v206, s52, v52
	v_fma_f32 v113, v207, s52, v53
	v_add_f32_e32 v104, v132, v104
	v_add_f32_e32 v105, v133, v105
	v_exp_f32_e32 v112, v112
	v_exp_f32_e32 v113, v113
	v_fma_f32 v106, v202, s52, v52
	v_fma_f32 v107, v203, s52, v53
	v_exp_f32_e32 v106, v106
	v_exp_f32_e32 v107, v107
	v_fma_f32 v108, v204, s52, v52
	v_fma_f32 v109, v205, s52, v53
	v_add_f32_e64 v114, v118, v104
	v_add_f32_e64 v115, v119, v105
	v_exp_f32_e32 v108, v108
	v_exp_f32_e32 v109, v109
	v_add_f32_e64 v116, v106, 0
	v_add_f32_e64 v117, v107, 0
	v_cvt_pk_bf16_f32 v104, v106, v107
	v_add_f32_e32 v106, v108, v116
	v_add_f32_e32 v107, v109, v117
	v_cvt_pk_bf16_f32 v105, v108, v109
	v_fma_f32 v100, v208, s52, v52
	v_fma_f32 v101, v209, s52, v53
	v_add_f32_e64 v102, v112, v106
	v_add_f32_e64 v103, v113, v107
	v_exp_f32_e32 v100, v100
	v_exp_f32_e32 v101, v101
	v_cvt_pk_bf16_f32 v106, v112, v113
	v_cvt_pk_bf16_f32 v107, v100, v101
	v_add_f32_e64 v100, v100, v102
	v_add_f32_e64 v101, v101, v103
	v_mfma_f32_32x32x16_bf16 a[16:31], v[178:181], v[104:107], a[16:31]
	v_add_f32_e32 v62, v62, v63
	v_add_f32_e32 v74, v74, v75
	v_add_f32_e32 v64, v64, v65
	v_add_f32_e32 v120, v120, v121
	v_add_f32_e32 v66, v66, v67
	v_add_f32_e32 v114, v114, v115
	v_mfma_f32_32x32x16_bf16 a[48:63], v[182:185], v[104:107], a[48:63]
	v_add_f32_e32 v68, v68, v69
	v_add_f32_e32 v100, v100, v101
	v_add_f32_e32 v62, v130, v62
	v_add_f32_e32 v74, v131, v74
	v_add_f32_e32 v62, v64, v62
	v_add_f32_e32 v74, v120, v74
	v_mfma_f32_32x32x16_bf16 a[80:95], v[186:189], v[104:107], a[80:95]
	v_add_f32_e32 v62, v66, v62
	v_add_f32_e32 v74, v114, v74
	v_add_f32_e32 v130, v68, v62
	v_add_f32_e32 v131, v100, v74
	v_mfma_f32_32x32x16_bf16 a[112:127], v[190:193], v[104:107], a[112:127]
	s_branch .Lattn_tail
.LBB0_245:
	s_lshl_b32 s38, s100, 6
	s_add_i32 s8, s38, s28
	s_mul_hi_i32 s9, s8, 0xc00
	s_mulk_i32 s8, 0xc00
	s_or_b64 s[8:9], s[8:9], s[2:3]
	v_lshl_add_u64 v[54:55], s[8:9], 1, v[50:51]
	s_add_i32 s8, s30, s38
	s_mul_hi_i32 s9, s8, 0xc00
	s_mulk_i32 s8, 0xc00
	s_or_b64 s[8:9], s[8:9], s[2:3]
	v_lshl_add_u64 v[56:57], s[8:9], 1, v[50:51]
	s_add_i32 s8, s31, s38
	s_mul_hi_i32 s9, s8, 0xc00
	s_mulk_i32 s8, 0xc00
	s_or_b64 s[8:9], s[8:9], s[2:3]
	v_lshl_add_u64 v[58:59], s[8:9], 1, v[50:51]
	s_add_i32 s8, s34, s38
	s_mul_hi_i32 s9, s8, 0xc00
	s_mulk_i32 s8, 0xc00
	s_or_b64 s[8:9], s[8:9], s[2:3]
	global_load_dwordx4 a[160:163], v[54:55], off
	global_load_dwordx4 a[164:167], v[56:57], off
	v_lshl_add_u64 v[60:61], s[8:9], 1, v[50:51]
	global_load_dwordx4 a[168:171], v[58:59], off
	global_load_dwordx4 a[172:175], v[60:61], off
	global_load_dwordx4 a[144:147], v[54:55], off offset:1024
	global_load_dwordx4 a[148:151], v[56:57], off offset:1024
	global_load_dwordx4 a[152:155], v[58:59], off offset:1024
	global_load_dwordx4 a[156:159], v[60:61], off offset:1024
	s_andn2_b32 s8, 1, s37
	s_mul_i32 s8, s8, 0x9400
	s_add_i32 s8, s8, 16
	s_waitcnt vmcnt(0)
	v_add3_u32 v54, s8, v77, v76
	ds_write_b128 v54, a[160:163]
	v_add3_u32 v55, s8, v78, v76
	ds_write_b128 v55, a[144:147] offset:17408
	v_add3_u32 v56, s8, v79, v76
	ds_write_b128 v56, a[164:167]
	v_add3_u32 v57, s8, v80, v76
	ds_write_b128 v57, a[148:151] offset:17408
	v_add3_u32 v58, s8, v81, v76
	ds_write_b128 v58, a[168:171]
	v_add3_u32 v59, s8, v82, v76
	ds_write_b128 v59, a[152:155] offset:17408
	v_add3_u32 v60, s8, v83, v76
	ds_write_b128 v60, a[172:175]
	v_add3_u32 v61, s8, v84, v76
	ds_write_b128 v61, a[156:159] offset:17408
